# GEMM K-loops: LDS-DMA pieces issued before the load segment's ds_read burst
# baseline (speedup 1.0000x reference)
.Lcar_367:
	s_add_u32 s36, s34, 0xfffc0080
	s_addc_u32 s37, s35, -1
	s_cmp_eq_u32 s65, 12
	s_cselect_b32 s39, s1, s37
	s_cselect_b32 s38, s25, s36
	s_cselect_b32 s37, s23, s41
	s_cselect_b32 s36, s31, s40
	s_add_u32 s70, s38, 0x80
	s_addc_u32 s71, s39, 0
	s_add_i32 m0, s47, 0xc000
	s_nop 0
	global_load_lds_dwordx4 v158, s[34:35]
	s_add_i32 m0, s47, 0xe000
	s_nop 0
	global_load_lds_dwordx4 v160, s[34:35]
	ds_read_b128 v[130:133], v168
	ds_read_b128 v[134:137], v168 offset:1024
	ds_read_b128 v[138:141], v168 offset:2048
	ds_read_b128 v[142:145], v168 offset:3072
	ds_read_b128 v[172:175], v169
	ds_read_b128 v[176:179], v169 offset:1024
	ds_read_b128 v[180:183], v169 offset:2048
	ds_read_b128 v[184:187], v169 offset:3072
	ds_read_b128 v[188:191], v170
	ds_read_b128 v[192:195], v170 offset:1024
	ds_read_b128 v[196:199], v170 offset:2048
	ds_read_b128 v[200:203], v170 offset:3072
	ds_read_b128 v[204:207], v170 offset:4096
	ds_read_b128 v[208:211], v170 offset:5120
	ds_read_b128 v[212:215], v170 offset:6144
	ds_read_b128 v[216:219], v170 offset:7168
	s_waitcnt vmcnt(8)
	s_waitcnt lgkmcnt(0)
	s_barrier
	s_setprio 1
	s_waitcnt lgkmcnt(0)
	v_mfma_f32_16x16x32_bf16 v[126:129], v[130:133], v[188:191], v[126:129]
	v_mfma_f32_16x16x32_bf16 v[122:125], v[138:141], v[188:191], v[122:125]
	v_mfma_f32_16x16x32_bf16 v[110:113], v[130:133], v[196:199], v[110:113]
	v_mfma_f32_16x16x32_bf16 v[106:109], v[138:141], v[196:199], v[106:109]
	v_mfma_f32_16x16x32_bf16 v[94:97], v[130:133], v[204:207], v[94:97]
	v_mfma_f32_16x16x32_bf16 v[90:93], v[138:141], v[204:207], v[90:93]
	v_mfma_f32_16x16x32_bf16 v[78:81], v[130:133], v[212:215], v[78:81]
	v_mfma_f32_16x16x32_bf16 v[74:77], v[138:141], v[212:215], v[74:77]
	v_mfma_f32_16x16x32_bf16 v[126:129], v[134:137], v[192:195], v[126:129]
	v_mfma_f32_16x16x32_bf16 v[122:125], v[142:145], v[192:195], v[122:125]
	v_mfma_f32_16x16x32_bf16 v[110:113], v[134:137], v[200:203], v[110:113]
	v_mfma_f32_16x16x32_bf16 v[106:109], v[142:145], v[200:203], v[106:109]
	v_mfma_f32_16x16x32_bf16 v[94:97], v[134:137], v[208:211], v[94:97]
	v_mfma_f32_16x16x32_bf16 v[90:93], v[142:145], v[208:211], v[90:93]
	v_mfma_f32_16x16x32_bf16 v[78:81], v[134:137], v[216:219], v[78:81]
	v_mfma_f32_16x16x32_bf16 v[74:77], v[142:145], v[216:219], v[74:77]
	s_setprio 0
	s_setprio 1
	v_mfma_f32_16x16x32_bf16 v[118:121], v[172:175], v[188:191], v[118:121]
	v_mfma_f32_16x16x32_bf16 v[114:117], v[180:183], v[188:191], v[114:117]
	v_mfma_f32_16x16x32_bf16 v[102:105], v[172:175], v[196:199], v[102:105]
	v_mfma_f32_16x16x32_bf16 v[98:101], v[180:183], v[196:199], v[98:101]
	v_mfma_f32_16x16x32_bf16 v[86:89], v[172:175], v[204:207], v[86:89]
	v_mfma_f32_16x16x32_bf16 v[82:85], v[180:183], v[204:207], v[82:85]
	v_mfma_f32_16x16x32_bf16 v[70:73], v[172:175], v[212:215], v[70:73]
	v_mfma_f32_16x16x32_bf16 v[66:69], v[180:183], v[212:215], v[66:69]
	v_mfma_f32_16x16x32_bf16 v[118:121], v[176:179], v[192:195], v[118:121]
	v_mfma_f32_16x16x32_bf16 v[114:117], v[184:187], v[192:195], v[114:117]
	v_mfma_f32_16x16x32_bf16 v[102:105], v[176:179], v[200:203], v[102:105]
	v_mfma_f32_16x16x32_bf16 v[98:101], v[184:187], v[200:203], v[98:101]
	v_mfma_f32_16x16x32_bf16 v[86:89], v[176:179], v[208:211], v[86:89]
	v_mfma_f32_16x16x32_bf16 v[82:85], v[184:187], v[208:211], v[82:85]
	v_mfma_f32_16x16x32_bf16 v[70:73], v[176:179], v[216:219], v[70:73]
	v_mfma_f32_16x16x32_bf16 v[66:69], v[184:187], v[216:219], v[66:69]
	s_setprio 0
	s_barrier
	s_add_i32 s66, s61, s46
	s_mov_b32 m0, s66
	s_nop 0
	global_load_lds_dwordx4 v148, s[36:37]
	s_add_i32 m0, s66, 0x2000
	s_add_u32 s66, s36, 0x10000
	s_addc_u32 s67, s37, 0
	s_add_i32 s68, s62, s46
	global_load_lds_dwordx4 v152, s[36:37]
	s_mov_b32 m0, s68
	s_nop 0
	global_load_lds_dwordx4 v148, s[66:67]
	s_add_i32 m0, s68, 0x2000
	s_nop 0
	global_load_lds_dwordx4 v152, s[66:67]
	s_mov_b32 m0, s47
	s_nop 0
	global_load_lds_dwordx4 v146, s[38:39]
	ds_read_b128 v[188:191], v170 offset:16384
	ds_read_b128 v[192:195], v170 offset:17408
	ds_read_b128 v[196:199], v170 offset:18432
	ds_read_b128 v[200:203], v170 offset:19456
	ds_read_b128 v[204:207], v170 offset:20480
	ds_read_b128 v[208:211], v170 offset:21504
	ds_read_b128 v[212:215], v170 offset:22528
	ds_read_b128 v[216:219], v170 offset:23552
	s_waitcnt vmcnt(7)
	s_waitcnt lgkmcnt(0)
	s_barrier
	s_setprio 1
	s_waitcnt lgkmcnt(0)
	v_mfma_f32_16x16x32_bf16 v[62:65], v[130:133], v[188:191], v[62:65]
	v_mfma_f32_16x16x32_bf16 v[58:61], v[138:141], v[188:191], v[58:61]
	v_mfma_f32_16x16x32_bf16 v[46:49], v[130:133], v[196:199], v[46:49]
	v_mfma_f32_16x16x32_bf16 v[42:45], v[138:141], v[196:199], v[42:45]
	v_mfma_f32_16x16x32_bf16 v[30:33], v[130:133], v[204:207], v[30:33]
	v_mfma_f32_16x16x32_bf16 v[26:29], v[138:141], v[204:207], v[26:29]
	v_mfma_f32_16x16x32_bf16 v[14:17], v[130:133], v[212:215], v[14:17]
	v_mfma_f32_16x16x32_bf16 v[10:13], v[138:141], v[212:215], v[10:13]
	v_mfma_f32_16x16x32_bf16 v[62:65], v[134:137], v[192:195], v[62:65]
	v_mfma_f32_16x16x32_bf16 v[58:61], v[142:145], v[192:195], v[58:61]
	v_mfma_f32_16x16x32_bf16 v[46:49], v[134:137], v[200:203], v[46:49]
	v_mfma_f32_16x16x32_bf16 v[42:45], v[142:145], v[200:203], v[42:45]
	v_mfma_f32_16x16x32_bf16 v[30:33], v[134:137], v[208:211], v[30:33]
	v_mfma_f32_16x16x32_bf16 v[26:29], v[142:145], v[208:211], v[26:29]
	v_mfma_f32_16x16x32_bf16 v[14:17], v[134:137], v[216:219], v[14:17]
	v_mfma_f32_16x16x32_bf16 v[10:13], v[142:145], v[216:219], v[10:13]
	s_setprio 0
	s_setprio 1
	v_mfma_f32_16x16x32_bf16 v[54:57], v[172:175], v[188:191], v[54:57]
	v_mfma_f32_16x16x32_bf16 v[50:53], v[180:183], v[188:191], v[50:53]
	v_mfma_f32_16x16x32_bf16 v[38:41], v[172:175], v[196:199], v[38:41]
	v_mfma_f32_16x16x32_bf16 v[34:37], v[180:183], v[196:199], v[34:37]
	v_mfma_f32_16x16x32_bf16 v[22:25], v[172:175], v[204:207], v[22:25]
	v_mfma_f32_16x16x32_bf16 v[18:21], v[180:183], v[204:207], v[18:21]
	v_mfma_f32_16x16x32_bf16 v[6:9], v[172:175], v[212:215], v[6:9]
	v_mfma_f32_16x16x32_bf16 v[2:5], v[180:183], v[212:215], v[2:5]
	v_mfma_f32_16x16x32_bf16 v[54:57], v[176:179], v[192:195], v[54:57]
	v_mfma_f32_16x16x32_bf16 v[50:53], v[184:187], v[192:195], v[50:53]
	v_mfma_f32_16x16x32_bf16 v[38:41], v[176:179], v[200:203], v[38:41]
	v_mfma_f32_16x16x32_bf16 v[34:37], v[184:187], v[200:203], v[34:37]
	v_mfma_f32_16x16x32_bf16 v[22:25], v[176:179], v[208:211], v[22:25]
	v_mfma_f32_16x16x32_bf16 v[18:21], v[184:187], v[208:211], v[18:21]
	v_mfma_f32_16x16x32_bf16 v[6:9], v[176:179], v[216:219], v[6:9]
	v_mfma_f32_16x16x32_bf16 v[2:5], v[184:187], v[216:219], v[2:5]
	s_setprio 0
	s_barrier
	s_add_i32 s66, 0, 0x18000
	s_add_i32 s67, 0, 0x1c000
	v_add_u32_e32 v142, s66, v157
	v_add_u32_e32 v154, s67, v157
	s_mov_b32 m0, s48
	s_nop 0
	global_load_lds_dwordx4 v150, s[38:39]
	s_add_u32 s38, s38, 0x40000
	s_addc_u32 s39, s39, 0
	s_mov_b32 m0, s49
	s_nop 0
	global_load_lds_dwordx4 v146, s[38:39]
	s_mov_b32 m0, s50
	s_nop 0
	global_load_lds_dwordx4 v150, s[38:39]
	ds_read_b128 v[130:133], v142
	ds_read_b128 v[134:137], v142 offset:1024
	ds_read_b128 v[138:141], v142 offset:2048
	ds_read_b128 v[142:145], v142 offset:3072
	ds_read_b128 v[172:175], v154
	ds_read_b128 v[176:179], v154 offset:1024
	ds_read_b128 v[180:183], v154 offset:2048
	ds_read_b128 v[184:187], v154 offset:3072
	ds_read_b128 v[188:191], v170 offset:32768
	ds_read_b128 v[192:195], v170 offset:33792
	ds_read_b128 v[196:199], v170 offset:34816
	ds_read_b128 v[200:203], v170 offset:35840
	ds_read_b128 v[204:207], v170 offset:36864
	ds_read_b128 v[208:211], v170 offset:37888
	ds_read_b128 v[212:215], v170 offset:38912
	ds_read_b128 v[216:219], v170 offset:39936
	s_waitcnt vmcnt(8)
	s_waitcnt lgkmcnt(0)
	s_barrier
	s_setprio 1
	s_waitcnt lgkmcnt(0)
	v_mfma_f32_16x16x32_bf16 v[126:129], v[130:133], v[188:191], v[126:129]
	v_mfma_f32_16x16x32_bf16 v[122:125], v[138:141], v[188:191], v[122:125]
	v_mfma_f32_16x16x32_bf16 v[110:113], v[130:133], v[196:199], v[110:113]
	v_mfma_f32_16x16x32_bf16 v[106:109], v[138:141], v[196:199], v[106:109]
	v_mfma_f32_16x16x32_bf16 v[94:97], v[130:133], v[204:207], v[94:97]
	v_mfma_f32_16x16x32_bf16 v[90:93], v[138:141], v[204:207], v[90:93]
	v_mfma_f32_16x16x32_bf16 v[78:81], v[130:133], v[212:215], v[78:81]
	v_mfma_f32_16x16x32_bf16 v[74:77], v[138:141], v[212:215], v[74:77]
	v_mfma_f32_16x16x32_bf16 v[126:129], v[134:137], v[192:195], v[126:129]
	v_mfma_f32_16x16x32_bf16 v[122:125], v[142:145], v[192:195], v[122:125]
	v_mfma_f32_16x16x32_bf16 v[110:113], v[134:137], v[200:203], v[110:113]
	v_mfma_f32_16x16x32_bf16 v[106:109], v[142:145], v[200:203], v[106:109]
	v_mfma_f32_16x16x32_bf16 v[94:97], v[134:137], v[208:211], v[94:97]
	v_mfma_f32_16x16x32_bf16 v[90:93], v[142:145], v[208:211], v[90:93]
	v_mfma_f32_16x16x32_bf16 v[78:81], v[134:137], v[216:219], v[78:81]
	v_mfma_f32_16x16x32_bf16 v[74:77], v[142:145], v[216:219], v[74:77]
	s_setprio 0
	s_setprio 1
	v_mfma_f32_16x16x32_bf16 v[118:121], v[172:175], v[188:191], v[118:121]
	v_mfma_f32_16x16x32_bf16 v[114:117], v[180:183], v[188:191], v[114:117]
	v_mfma_f32_16x16x32_bf16 v[102:105], v[172:175], v[196:199], v[102:105]
	v_mfma_f32_16x16x32_bf16 v[98:101], v[180:183], v[196:199], v[98:101]
	v_mfma_f32_16x16x32_bf16 v[86:89], v[172:175], v[204:207], v[86:89]
	v_mfma_f32_16x16x32_bf16 v[82:85], v[180:183], v[204:207], v[82:85]
	v_mfma_f32_16x16x32_bf16 v[70:73], v[172:175], v[212:215], v[70:73]
	v_mfma_f32_16x16x32_bf16 v[66:69], v[180:183], v[212:215], v[66:69]
	v_mfma_f32_16x16x32_bf16 v[118:121], v[176:179], v[192:195], v[118:121]
	v_mfma_f32_16x16x32_bf16 v[114:117], v[184:187], v[192:195], v[114:117]
	v_mfma_f32_16x16x32_bf16 v[102:105], v[176:179], v[200:203], v[102:105]
	v_mfma_f32_16x16x32_bf16 v[98:101], v[184:187], v[200:203], v[98:101]
	v_mfma_f32_16x16x32_bf16 v[86:89], v[176:179], v[208:211], v[86:89]
	v_mfma_f32_16x16x32_bf16 v[82:85], v[184:187], v[208:211], v[82:85]
	v_mfma_f32_16x16x32_bf16 v[70:73], v[176:179], v[216:219], v[70:73]
	v_mfma_f32_16x16x32_bf16 v[66:69], v[184:187], v[216:219], v[66:69]
	s_setprio 0
	s_barrier
	s_add_i32 s38, s66, s46
	s_mov_b32 m0, s38
	s_add_u32 s36, s36, 0x80
	s_addc_u32 s37, s37, 0
	global_load_lds_dwordx4 v148, s[36:37]
	s_add_i32 m0, s38, 0x2000
	s_add_i32 s38, s67, s46
	global_load_lds_dwordx4 v152, s[36:37]
	s_add_u32 s36, s36, 0x10000
	s_addc_u32 s37, s37, 0
	s_mov_b32 m0, s38
	s_nop 0
	global_load_lds_dwordx4 v148, s[36:37]
	s_add_i32 m0, s38, 0x2000
	s_nop 0
	global_load_lds_dwordx4 v152, s[36:37]
	s_mov_b32 m0, s56
	s_nop 0
	global_load_lds_dwordx4 v146, s[70:71]
	ds_read_b128 v[188:191], v170 offset:49152
	ds_read_b128 v[192:195], v170 offset:50176
	ds_read_b128 v[196:199], v170 offset:51200
	ds_read_b128 v[200:203], v170 offset:52224
	ds_read_b128 v[204:207], v170 offset:53248
	ds_read_b128 v[208:211], v170 offset:54272
	ds_read_b128 v[212:215], v170 offset:55296
	ds_read_b128 v[216:219], v170 offset:56320
	s_waitcnt vmcnt(7)
	s_waitcnt lgkmcnt(0)
	s_barrier
	s_setprio 1
	s_waitcnt lgkmcnt(0)
	v_mfma_f32_16x16x32_bf16 v[62:65], v[130:133], v[188:191], v[62:65]
	v_mfma_f32_16x16x32_bf16 v[58:61], v[138:141], v[188:191], v[58:61]
	v_mfma_f32_16x16x32_bf16 v[46:49], v[130:133], v[196:199], v[46:49]
	v_mfma_f32_16x16x32_bf16 v[42:45], v[138:141], v[196:199], v[42:45]
	v_mfma_f32_16x16x32_bf16 v[30:33], v[130:133], v[204:207], v[30:33]
	v_mfma_f32_16x16x32_bf16 v[26:29], v[138:141], v[204:207], v[26:29]
	v_mfma_f32_16x16x32_bf16 v[14:17], v[130:133], v[212:215], v[14:17]
	v_mfma_f32_16x16x32_bf16 v[10:13], v[138:141], v[212:215], v[10:13]
	v_mfma_f32_16x16x32_bf16 v[62:65], v[134:137], v[192:195], v[62:65]
	v_mfma_f32_16x16x32_bf16 v[58:61], v[142:145], v[192:195], v[58:61]
	v_mfma_f32_16x16x32_bf16 v[46:49], v[134:137], v[200:203], v[46:49]
	v_mfma_f32_16x16x32_bf16 v[42:45], v[142:145], v[200:203], v[42:45]
	v_mfma_f32_16x16x32_bf16 v[30:33], v[134:137], v[208:211], v[30:33]
	v_mfma_f32_16x16x32_bf16 v[26:29], v[142:145], v[208:211], v[26:29]
	v_mfma_f32_16x16x32_bf16 v[14:17], v[134:137], v[216:219], v[14:17]
	v_mfma_f32_16x16x32_bf16 v[10:13], v[142:145], v[216:219], v[10:13]
	s_setprio 0
	s_setprio 1
	v_mfma_f32_16x16x32_bf16 v[54:57], v[172:175], v[188:191], v[54:57]
	v_mfma_f32_16x16x32_bf16 v[50:53], v[180:183], v[188:191], v[50:53]
	v_mfma_f32_16x16x32_bf16 v[38:41], v[172:175], v[196:199], v[38:41]
	v_mfma_f32_16x16x32_bf16 v[34:37], v[180:183], v[196:199], v[34:37]
	v_mfma_f32_16x16x32_bf16 v[22:25], v[172:175], v[204:207], v[22:25]
	s_add_i32 s65, s65, 2
	v_mfma_f32_16x16x32_bf16 v[18:21], v[180:183], v[204:207], v[18:21]
	v_mfma_f32_16x16x32_bf16 v[6:9], v[172:175], v[212:215], v[6:9]
	s_add_u32 s34, s34, 0x100
	s_addc_u32 s35, s35, 0
	v_mfma_f32_16x16x32_bf16 v[2:5], v[180:183], v[212:215], v[2:5]
	v_mfma_f32_16x16x32_bf16 v[54:57], v[176:179], v[192:195], v[54:57]
	s_add_u32 s40, s40, 0x100
	s_addc_u32 s41, s41, 0
	v_mfma_f32_16x16x32_bf16 v[50:53], v[184:187], v[192:195], v[50:53]
	v_mfma_f32_16x16x32_bf16 v[38:41], v[176:179], v[200:203], v[38:41]
	s_cmp_gt_u32 s65, 13
	v_mfma_f32_16x16x32_bf16 v[34:37], v[184:187], v[200:203], v[34:37]
	v_mfma_f32_16x16x32_bf16 v[22:25], v[176:179], v[208:211], v[22:25]
	v_mfma_f32_16x16x32_bf16 v[18:21], v[184:187], v[208:211], v[18:21]
	v_mfma_f32_16x16x32_bf16 v[6:9], v[176:179], v[216:219], v[6:9]
	v_mfma_f32_16x16x32_bf16 v[2:5], v[184:187], v[216:219], v[2:5]
	s_setprio 0
	s_barrier
	s_cbranch_scc0 .LBB0_367
	s_mov_b32 m0, s57
	s_nop 0
	global_load_lds_dwordx4 v150, s[70:71]
	s_and_b64 vcc, exec, s[20:21]
	s_cbranch_vccz .LBB0_370
	s_barrier

.Lcar_766:
	s_add_u32 s38, s36, 0xfffc0080
	s_addc_u32 s39, s37, -1
	s_cmp_eq_u32 s63, 12
	s_cselect_b32 s41, s27, s39
	s_cselect_b32 s40, s59, s38
	s_cselect_b32 s39, s25, s62
	s_cselect_b32 s38, s60, s61
	s_add_u32 s68, s40, 0x80
	s_addc_u32 s69, s41, 0
	s_add_i32 m0, s35, 0xc000
	s_nop 0
	global_load_lds_dwordx4 v148, s[36:37]
	s_add_i32 m0, s35, 0xe000
	s_nop 0
	global_load_lds_dwordx4 v150, s[36:37]
	ds_read_b128 v[128:131], v163
	ds_read_b128 v[132:135], v163 offset:1024
	ds_read_b128 v[136:139], v163 offset:2048
	ds_read_b128 v[140:143], v163 offset:3072
	ds_read_b128 v[156:159], v164
	ds_read_b128 v[166:169], v164 offset:1024
	ds_read_b128 v[170:173], v164 offset:2048
	ds_read_b128 v[174:177], v164 offset:3072
	ds_read_b128 v[178:181], v165
	ds_read_b128 v[182:185], v165 offset:1024
	ds_read_b128 v[186:189], v165 offset:2048
	ds_read_b128 v[190:193], v165 offset:3072
	ds_read_b128 v[194:197], v165 offset:4096
	ds_read_b128 v[198:201], v165 offset:5120
	ds_read_b128 v[202:205], v165 offset:6144
	ds_read_b128 v[206:209], v165 offset:7168
	s_waitcnt vmcnt(8)
	s_waitcnt lgkmcnt(0)
	s_barrier
	s_setprio 1
	s_waitcnt lgkmcnt(0)
	v_mfma_f32_16x16x32_bf16 v[124:127], v[128:131], v[178:181], v[124:127]
	v_mfma_f32_16x16x32_bf16 v[120:123], v[136:139], v[178:181], v[120:123]
	v_mfma_f32_16x16x32_bf16 v[116:119], v[128:131], v[186:189], v[116:119]
	v_mfma_f32_16x16x32_bf16 v[108:111], v[136:139], v[186:189], v[108:111]
	v_mfma_f32_16x16x32_bf16 v[96:99], v[128:131], v[194:197], v[96:99]
	v_mfma_f32_16x16x32_bf16 v[88:91], v[136:139], v[194:197], v[88:91]
	v_mfma_f32_16x16x32_bf16 v[84:87], v[128:131], v[202:205], v[84:87]
	v_mfma_f32_16x16x32_bf16 v[76:79], v[136:139], v[202:205], v[76:79]
	v_mfma_f32_16x16x32_bf16 v[124:127], v[132:135], v[182:185], v[124:127]
	v_mfma_f32_16x16x32_bf16 v[120:123], v[140:143], v[182:185], v[120:123]
	v_mfma_f32_16x16x32_bf16 v[116:119], v[132:135], v[190:193], v[116:119]
	v_mfma_f32_16x16x32_bf16 v[108:111], v[140:143], v[190:193], v[108:111]
	v_mfma_f32_16x16x32_bf16 v[96:99], v[132:135], v[198:201], v[96:99]
	v_mfma_f32_16x16x32_bf16 v[88:91], v[140:143], v[198:201], v[88:91]
	v_mfma_f32_16x16x32_bf16 v[84:87], v[132:135], v[206:209], v[84:87]
	v_mfma_f32_16x16x32_bf16 v[76:79], v[140:143], v[206:209], v[76:79]
	s_setprio 0
	s_setprio 1
	v_mfma_f32_16x16x32_bf16 v[112:115], v[156:159], v[178:181], v[112:115]
	v_mfma_f32_16x16x32_bf16 v[104:107], v[170:173], v[178:181], v[104:107]
	v_mfma_f32_16x16x32_bf16 v[100:103], v[156:159], v[186:189], v[100:103]
	v_mfma_f32_16x16x32_bf16 v[92:95], v[170:173], v[186:189], v[92:95]
	v_mfma_f32_16x16x32_bf16 v[80:83], v[156:159], v[194:197], v[80:83]
	v_mfma_f32_16x16x32_bf16 v[72:75], v[170:173], v[194:197], v[72:75]
	v_mfma_f32_16x16x32_bf16 v[68:71], v[156:159], v[202:205], v[68:71]
	v_mfma_f32_16x16x32_bf16 v[64:67], v[170:173], v[202:205], v[64:67]
	v_mfma_f32_16x16x32_bf16 v[112:115], v[166:169], v[182:185], v[112:115]
	v_mfma_f32_16x16x32_bf16 v[104:107], v[174:177], v[182:185], v[104:107]
	v_mfma_f32_16x16x32_bf16 v[100:103], v[166:169], v[190:193], v[100:103]
	v_mfma_f32_16x16x32_bf16 v[92:95], v[174:177], v[190:193], v[92:95]
	v_mfma_f32_16x16x32_bf16 v[80:83], v[166:169], v[198:201], v[80:83]
	v_mfma_f32_16x16x32_bf16 v[72:75], v[174:177], v[198:201], v[72:75]
	v_mfma_f32_16x16x32_bf16 v[68:71], v[166:169], v[206:209], v[68:71]
	v_mfma_f32_16x16x32_bf16 v[64:67], v[174:177], v[206:209], v[64:67]
	s_setprio 0
	s_barrier
	s_add_i32 s64, s55, s46
	s_mov_b32 m0, s64
	s_nop 0
	global_load_lds_dwordx4 v144, s[38:39]
	s_add_i32 m0, s64, 0x2000
	s_add_u32 s64, s38, 0x40000
	s_addc_u32 s65, s39, 0
	s_add_i32 s66, s56, s46
	global_load_lds_dwordx4 v146, s[38:39]
	s_mov_b32 m0, s66
	s_nop 0
	global_load_lds_dwordx4 v144, s[64:65]
	s_add_i32 m0, s66, 0x2000
	s_nop 0
	global_load_lds_dwordx4 v146, s[64:65]
	s_mov_b32 m0, s35
	s_nop 0
	global_load_lds_dwordx4 v144, s[40:41]
	ds_read_b128 v[178:181], v165 offset:16384
	ds_read_b128 v[182:185], v165 offset:17408
	ds_read_b128 v[186:189], v165 offset:18432
	ds_read_b128 v[190:193], v165 offset:19456
	ds_read_b128 v[194:197], v165 offset:20480
	ds_read_b128 v[198:201], v165 offset:21504
	ds_read_b128 v[202:205], v165 offset:22528
	ds_read_b128 v[206:209], v165 offset:23552
	s_waitcnt vmcnt(7)
	s_waitcnt lgkmcnt(0)
	s_barrier
	s_setprio 1
	s_waitcnt lgkmcnt(0)
	v_mfma_f32_16x16x32_bf16 v[60:63], v[128:131], v[178:181], v[60:63]
	v_mfma_f32_16x16x32_bf16 v[56:59], v[136:139], v[178:181], v[56:59]
	v_mfma_f32_16x16x32_bf16 v[52:55], v[128:131], v[186:189], v[52:55]
	v_mfma_f32_16x16x32_bf16 v[44:47], v[136:139], v[186:189], v[44:47]
	v_mfma_f32_16x16x32_bf16 v[36:39], v[128:131], v[194:197], v[36:39]
	v_mfma_f32_16x16x32_bf16 v[28:31], v[136:139], v[194:197], v[28:31]
	v_mfma_f32_16x16x32_bf16 v[20:23], v[128:131], v[202:205], v[20:23]
	v_mfma_f32_16x16x32_bf16 v[12:15], v[136:139], v[202:205], v[12:15]
	v_mfma_f32_16x16x32_bf16 v[60:63], v[132:135], v[182:185], v[60:63]
	v_mfma_f32_16x16x32_bf16 v[56:59], v[140:143], v[182:185], v[56:59]
	v_mfma_f32_16x16x32_bf16 v[52:55], v[132:135], v[190:193], v[52:55]
	v_mfma_f32_16x16x32_bf16 v[44:47], v[140:143], v[190:193], v[44:47]
	v_mfma_f32_16x16x32_bf16 v[36:39], v[132:135], v[198:201], v[36:39]
	v_mfma_f32_16x16x32_bf16 v[28:31], v[140:143], v[198:201], v[28:31]
	v_mfma_f32_16x16x32_bf16 v[20:23], v[132:135], v[206:209], v[20:23]
	v_mfma_f32_16x16x32_bf16 v[12:15], v[140:143], v[206:209], v[12:15]
	s_setprio 0
	s_setprio 1
	v_mfma_f32_16x16x32_bf16 v[48:51], v[156:159], v[178:181], v[48:51]
	v_mfma_f32_16x16x32_bf16 v[40:43], v[170:173], v[178:181], v[40:43]
	v_mfma_f32_16x16x32_bf16 v[32:35], v[156:159], v[186:189], v[32:35]
	v_mfma_f32_16x16x32_bf16 v[24:27], v[170:173], v[186:189], v[24:27]
	v_mfma_f32_16x16x32_bf16 v[16:19], v[156:159], v[194:197], v[16:19]
	v_mfma_f32_16x16x32_bf16 v[8:11], v[170:173], v[194:197], v[8:11]
	v_mfma_f32_16x16x32_bf16 v[4:7], v[156:159], v[202:205], v[4:7]
	v_mfma_f32_16x16x32_bf16 v[0:3], v[170:173], v[202:205], v[0:3]
	v_mfma_f32_16x16x32_bf16 v[48:51], v[166:169], v[182:185], v[48:51]
	v_mfma_f32_16x16x32_bf16 v[40:43], v[174:177], v[182:185], v[40:43]
	v_mfma_f32_16x16x32_bf16 v[32:35], v[166:169], v[190:193], v[32:35]
	v_mfma_f32_16x16x32_bf16 v[24:27], v[174:177], v[190:193], v[24:27]
	v_mfma_f32_16x16x32_bf16 v[16:19], v[166:169], v[198:201], v[16:19]
	v_mfma_f32_16x16x32_bf16 v[8:11], v[174:177], v[198:201], v[8:11]
	v_mfma_f32_16x16x32_bf16 v[4:7], v[166:169], v[206:209], v[4:7]
	v_mfma_f32_16x16x32_bf16 v[0:3], v[174:177], v[206:209], v[0:3]
	s_setprio 0
	s_barrier
	s_add_i32 s64, 0, 0x18000
	s_add_i32 s65, 0, 0x1c000
	v_add_u32_e32 v140, s64, v161
	v_add_u32_e32 v174, s65, v161
	s_mov_b32 m0, s47
	s_nop 0
	global_load_lds_dwordx4 v146, s[40:41]
	s_add_u32 s40, s40, 0x40000
	s_addc_u32 s41, s41, 0
	s_mov_b32 m0, s48
	s_nop 0
	global_load_lds_dwordx4 v144, s[40:41]
	s_mov_b32 m0, s49
	s_nop 0
	global_load_lds_dwordx4 v146, s[40:41]
	ds_read_b128 v[128:131], v140
	ds_read_b128 v[132:135], v140 offset:1024
	ds_read_b128 v[136:139], v140 offset:2048
	ds_read_b128 v[140:143], v140 offset:3072
	ds_read_b128 v[156:159], v174
	ds_read_b128 v[166:169], v174 offset:1024
	ds_read_b128 v[170:173], v174 offset:2048
	ds_read_b128 v[174:177], v174 offset:3072
	ds_read_b128 v[178:181], v165 offset:32768
	ds_read_b128 v[182:185], v165 offset:33792
	ds_read_b128 v[186:189], v165 offset:34816
	ds_read_b128 v[190:193], v165 offset:35840
	ds_read_b128 v[194:197], v165 offset:36864
	ds_read_b128 v[198:201], v165 offset:37888
	ds_read_b128 v[202:205], v165 offset:38912
	ds_read_b128 v[206:209], v165 offset:39936
	s_waitcnt vmcnt(8)
	s_waitcnt lgkmcnt(0)
	s_barrier
	s_setprio 1
	s_waitcnt lgkmcnt(0)
	v_mfma_f32_16x16x32_bf16 v[124:127], v[128:131], v[178:181], v[124:127]
	v_mfma_f32_16x16x32_bf16 v[120:123], v[136:139], v[178:181], v[120:123]
	v_mfma_f32_16x16x32_bf16 v[116:119], v[128:131], v[186:189], v[116:119]
	v_mfma_f32_16x16x32_bf16 v[108:111], v[136:139], v[186:189], v[108:111]
	v_mfma_f32_16x16x32_bf16 v[96:99], v[128:131], v[194:197], v[96:99]
	v_mfma_f32_16x16x32_bf16 v[88:91], v[136:139], v[194:197], v[88:91]
	v_mfma_f32_16x16x32_bf16 v[84:87], v[128:131], v[202:205], v[84:87]
	v_mfma_f32_16x16x32_bf16 v[76:79], v[136:139], v[202:205], v[76:79]
	v_mfma_f32_16x16x32_bf16 v[124:127], v[132:135], v[182:185], v[124:127]
	v_mfma_f32_16x16x32_bf16 v[120:123], v[140:143], v[182:185], v[120:123]
	v_mfma_f32_16x16x32_bf16 v[116:119], v[132:135], v[190:193], v[116:119]
	v_mfma_f32_16x16x32_bf16 v[108:111], v[140:143], v[190:193], v[108:111]
	v_mfma_f32_16x16x32_bf16 v[96:99], v[132:135], v[198:201], v[96:99]
	v_mfma_f32_16x16x32_bf16 v[88:91], v[140:143], v[198:201], v[88:91]
	v_mfma_f32_16x16x32_bf16 v[84:87], v[132:135], v[206:209], v[84:87]
	v_mfma_f32_16x16x32_bf16 v[76:79], v[140:143], v[206:209], v[76:79]
	s_setprio 0
	s_setprio 1
	v_mfma_f32_16x16x32_bf16 v[112:115], v[156:159], v[178:181], v[112:115]
	v_mfma_f32_16x16x32_bf16 v[104:107], v[170:173], v[178:181], v[104:107]
	v_mfma_f32_16x16x32_bf16 v[100:103], v[156:159], v[186:189], v[100:103]
	v_mfma_f32_16x16x32_bf16 v[92:95], v[170:173], v[186:189], v[92:95]
	v_mfma_f32_16x16x32_bf16 v[80:83], v[156:159], v[194:197], v[80:83]
	v_mfma_f32_16x16x32_bf16 v[72:75], v[170:173], v[194:197], v[72:75]
	v_mfma_f32_16x16x32_bf16 v[68:71], v[156:159], v[202:205], v[68:71]
	v_mfma_f32_16x16x32_bf16 v[64:67], v[170:173], v[202:205], v[64:67]
	v_mfma_f32_16x16x32_bf16 v[112:115], v[166:169], v[182:185], v[112:115]
	v_mfma_f32_16x16x32_bf16 v[104:107], v[174:177], v[182:185], v[104:107]
	v_mfma_f32_16x16x32_bf16 v[100:103], v[166:169], v[190:193], v[100:103]
	v_mfma_f32_16x16x32_bf16 v[92:95], v[174:177], v[190:193], v[92:95]
	v_mfma_f32_16x16x32_bf16 v[80:83], v[166:169], v[198:201], v[80:83]
	v_mfma_f32_16x16x32_bf16 v[72:75], v[174:177], v[198:201], v[72:75]
	v_mfma_f32_16x16x32_bf16 v[68:71], v[166:169], v[206:209], v[68:71]
	v_mfma_f32_16x16x32_bf16 v[64:67], v[174:177], v[206:209], v[64:67]
	s_setprio 0
	s_barrier
	s_add_i32 s40, s64, s46
	s_mov_b32 m0, s40
	s_add_u32 s38, s38, 0x80
	s_addc_u32 s39, s39, 0
	global_load_lds_dwordx4 v144, s[38:39]
	s_add_i32 m0, s40, 0x2000
	s_add_i32 s40, s65, s46
	global_load_lds_dwordx4 v146, s[38:39]
	s_add_u32 s38, s38, 0x40000
	s_addc_u32 s39, s39, 0
	s_mov_b32 m0, s40
	s_nop 0
	global_load_lds_dwordx4 v144, s[38:39]
	s_add_i32 m0, s40, 0x2000
	s_nop 0
	global_load_lds_dwordx4 v146, s[38:39]
	s_mov_b32 m0, s52
	s_nop 0
	global_load_lds_dwordx4 v144, s[68:69]
	ds_read_b128 v[178:181], v165 offset:49152
	ds_read_b128 v[182:185], v165 offset:50176
	ds_read_b128 v[186:189], v165 offset:51200
	ds_read_b128 v[190:193], v165 offset:52224
	ds_read_b128 v[194:197], v165 offset:53248
	ds_read_b128 v[198:201], v165 offset:54272
	ds_read_b128 v[202:205], v165 offset:55296
	ds_read_b128 v[206:209], v165 offset:56320
	s_waitcnt vmcnt(7)
	s_waitcnt lgkmcnt(0)
	s_barrier
	s_setprio 1
	s_waitcnt lgkmcnt(0)
	v_mfma_f32_16x16x32_bf16 v[60:63], v[128:131], v[178:181], v[60:63]
	v_mfma_f32_16x16x32_bf16 v[56:59], v[136:139], v[178:181], v[56:59]
	v_mfma_f32_16x16x32_bf16 v[52:55], v[128:131], v[186:189], v[52:55]
	v_mfma_f32_16x16x32_bf16 v[44:47], v[136:139], v[186:189], v[44:47]
	v_mfma_f32_16x16x32_bf16 v[36:39], v[128:131], v[194:197], v[36:39]
	v_mfma_f32_16x16x32_bf16 v[28:31], v[136:139], v[194:197], v[28:31]
	v_mfma_f32_16x16x32_bf16 v[20:23], v[128:131], v[202:205], v[20:23]
	v_mfma_f32_16x16x32_bf16 v[12:15], v[136:139], v[202:205], v[12:15]
	v_mfma_f32_16x16x32_bf16 v[60:63], v[132:135], v[182:185], v[60:63]
	v_mfma_f32_16x16x32_bf16 v[56:59], v[140:143], v[182:185], v[56:59]
	v_mfma_f32_16x16x32_bf16 v[52:55], v[132:135], v[190:193], v[52:55]
	v_mfma_f32_16x16x32_bf16 v[44:47], v[140:143], v[190:193], v[44:47]
	v_mfma_f32_16x16x32_bf16 v[36:39], v[132:135], v[198:201], v[36:39]
	v_mfma_f32_16x16x32_bf16 v[28:31], v[140:143], v[198:201], v[28:31]
	v_mfma_f32_16x16x32_bf16 v[20:23], v[132:135], v[206:209], v[20:23]
	v_mfma_f32_16x16x32_bf16 v[12:15], v[140:143], v[206:209], v[12:15]
	s_setprio 0
	s_setprio 1
	v_mfma_f32_16x16x32_bf16 v[48:51], v[156:159], v[178:181], v[48:51]
	v_mfma_f32_16x16x32_bf16 v[40:43], v[170:173], v[178:181], v[40:43]
	v_mfma_f32_16x16x32_bf16 v[32:35], v[156:159], v[186:189], v[32:35]
	v_mfma_f32_16x16x32_bf16 v[24:27], v[170:173], v[186:189], v[24:27]
	v_mfma_f32_16x16x32_bf16 v[16:19], v[156:159], v[194:197], v[16:19]
	s_add_i32 s63, s63, 2
	v_mfma_f32_16x16x32_bf16 v[8:11], v[170:173], v[194:197], v[8:11]
	v_mfma_f32_16x16x32_bf16 v[4:7], v[156:159], v[202:205], v[4:7]
	s_add_u32 s36, s36, 0x100
	s_addc_u32 s37, s37, 0
	v_mfma_f32_16x16x32_bf16 v[0:3], v[170:173], v[202:205], v[0:3]
	v_mfma_f32_16x16x32_bf16 v[48:51], v[166:169], v[182:185], v[48:51]
	s_add_u32 s61, s61, 0x100
	s_addc_u32 s62, s62, 0
	v_mfma_f32_16x16x32_bf16 v[40:43], v[174:177], v[182:185], v[40:43]
	v_mfma_f32_16x16x32_bf16 v[32:35], v[166:169], v[190:193], v[32:35]
	s_cmp_gt_u32 s63, 13
	v_mfma_f32_16x16x32_bf16 v[24:27], v[174:177], v[190:193], v[24:27]
	v_mfma_f32_16x16x32_bf16 v[16:19], v[166:169], v[198:201], v[16:19]
	v_mfma_f32_16x16x32_bf16 v[8:11], v[174:177], v[198:201], v[8:11]
	v_mfma_f32_16x16x32_bf16 v[4:7], v[166:169], v[206:209], v[4:7]
	v_mfma_f32_16x16x32_bf16 v[0:3], v[174:177], v[206:209], v[0:3]
	s_setprio 0
	s_barrier
	s_cbranch_scc0 .LBB0_766
	s_mov_b32 m0, s53
	s_nop 0
	global_load_lds_dwordx4 v146, s[68:69]
	s_and_b64 vcc, exec, s[12:13]
	s_cbranch_vccz .LBB0_769
	s_barrier
